# grid barriers: XCD leader issues its TOP arrival add before the L1 invalidate (the add releases the other workgroups and no longer queues behind the invalidate)
# speedup vs baseline: 1.0034x; 1.0025x over previous
; __device__ __forceinline__ unsigned xb_ld(unsigned* p)              { return __hip_atomic_load(p, __ATOMIC_RELAXED, __HIP_MEMORY_SCOPE_AGENT); }
; __device__ __forceinline__ unsigned xb_add(unsigned* p, unsigned v) { return __hip_atomic_fetch_add(p, v, __ATOMIC_RELAXED, __HIP_MEMORY_SCOPE_AGENT); }
; #define XB_SPIN(cond, bar) do { unsigned _sp = 0; while (cond) { __builtin_amdgcn_s_sleep(1); \
;     if ((++_sp & 255u) == 0u) { if (xb_ld(&(bar)[XB_TMO])) break; if (_sp > XB_SPIN_CAP) { atomicAdd(&(bar)[XB_TMO], 1u); break; } } } } while (0)
; __device__ __forceinline__ void xcd_barrier(const XcdBarrier& b) {
;     ...
;             const unsigned og = xb_add(&bar[XB_TOP], 1u);
;             const unsigned tg = og / nx;
;             if (og + 1u == (tg + 1u) * nx) xb_add(&bar[XB_TOPGEN], 1u);
;             else XB_SPIN(xb_ld(&bar[XB_TOPGEN]) == tg, bar);
;             __builtin_amdgcn_fence(__ATOMIC_ACQUIRE, "agent");
.LBB0_166:
	s_or_b64 exec, exec, s[10:11]
	buffer_inv sc1
	v_cvt_f32_u32_e32 v3, v0
	s_waitcnt vmcnt(0)
	v_readfirstlane_b32 s8, v2
	s_add_u32 s10, s70, 0x2303500
	s_addc_u32 s11, s71, 0
	v_rcp_iflag_f32_e32 v3, v3
	v_add_u32_e32 v1, s8, v1
	v_add_u32_e32 v4, 1, v1
	s_mov_b64 s[12:13], -1
	v_mul_f32_e32 v2, 0x4f7ffffe, v3
	v_cvt_u32_f32_e32 v2, v2
	v_sub_u32_e32 v3, 0, v0
	v_mul_lo_u32 v3, v3, v2
	v_mul_hi_u32 v3, v2, v3
	v_add_u32_e32 v2, v2, v3
	v_mul_hi_u32 v2, v1, v2
	v_mul_lo_u32 v3, v2, v0
	v_sub_u32_e32 v1, v1, v3
	v_add_u32_e32 v5, 1, v2
	v_cmp_ge_u32_e32 vcc, v1, v0
	v_sub_u32_e32 v3, v1, v0
	s_nop 0
	v_cndmask_b32_e32 v2, v2, v5, vcc
	v_cndmask_b32_e32 v1, v1, v3, vcc
	v_add_u32_e32 v3, 1, v2
	v_cmp_ge_u32_e32 vcc, v1, v0
	s_nop 1
	v_cndmask_b32_e32 v2, v2, v3, vcc
	v_mul_lo_u32 v1, v0, v2
	v_add_u32_e32 v0, v1, v0
	v_cmp_ne_u32_e32 vcc, v4, v0
	v_mov_b32_e32 v3, v0
	v_mov_b32_e32 v5, 0x2303000
	v_mov_b64_e32 v[0:1], s[10:11]
	s_and_saveexec_b64 s[8:9], vcc
	s_cbranch_execz .LBB0_178
	v_mov_b32_e32 v0, 0
	global_load_dword v1, v5, s[70:71] offset:1024 sc1
	s_mov_b64 s[20:21], 0
	s_waitcnt vmcnt(0)
	v_cmp_lt_u32_e32 vcc, v1, v3
	s_and_saveexec_b64 s[18:19], vcc
	s_cbranch_execz .LBB0_177
	s_add_u32 s12, s70, 0x2300200
	s_addc_u32 s13, s71, 0
	s_mov_b32 s14, 1
	s_branch .LBB0_170

; __device__ __forceinline__ unsigned xb_ld(unsigned* p)              { return __hip_atomic_load(p, __ATOMIC_RELAXED, __HIP_MEMORY_SCOPE_AGENT); }
; __device__ __forceinline__ unsigned xb_add(unsigned* p, unsigned v) { return __hip_atomic_fetch_add(p, v, __ATOMIC_RELAXED, __HIP_MEMORY_SCOPE_AGENT); }
; #define XB_SPIN(cond, bar) do { unsigned _sp = 0; while (cond) { __builtin_amdgcn_s_sleep(1); \
;     if ((++_sp & 255u) == 0u) { if (xb_ld(&(bar)[XB_TMO])) break; if (_sp > XB_SPIN_CAP) { atomicAdd(&(bar)[XB_TMO], 1u); break; } } } } while (0)
; __device__ __forceinline__ void xcd_barrier(const XcdBarrier& b) {
;     ...
;             const unsigned og = xb_add(&bar[XB_TOP], 1u);
;             const unsigned tg = og / nx;
;             if (og + 1u == (tg + 1u) * nx) xb_add(&bar[XB_TOPGEN], 1u);
;             else XB_SPIN(xb_ld(&bar[XB_TOPGEN]) == tg, bar);
;             __builtin_amdgcn_fence(__ATOMIC_ACQUIRE, "agent");
.LBB0_259:
	s_or_b64 exec, exec, s[8:9]
	buffer_inv sc1
	v_cvt_f32_u32_e32 v3, v0
	s_waitcnt vmcnt(0)
	v_readfirstlane_b32 s6, v2
	s_add_u32 s8, s70, 0x2303500
	s_addc_u32 s9, s71, 0
	v_rcp_iflag_f32_e32 v3, v3
	v_add_u32_e32 v1, s6, v1
	v_add_u32_e32 v4, 1, v1
	s_mov_b64 s[10:11], -1
	v_mul_f32_e32 v2, 0x4f7ffffe, v3
	v_cvt_u32_f32_e32 v2, v2
	v_sub_u32_e32 v3, 0, v0
	v_mul_lo_u32 v3, v3, v2
	v_mul_hi_u32 v3, v2, v3
	v_add_u32_e32 v2, v2, v3
	v_mul_hi_u32 v2, v1, v2
	v_mul_lo_u32 v3, v2, v0
	v_sub_u32_e32 v1, v1, v3
	v_add_u32_e32 v5, 1, v2
	v_cmp_ge_u32_e32 vcc, v1, v0
	v_sub_u32_e32 v3, v1, v0
	s_nop 0
	v_cndmask_b32_e32 v2, v2, v5, vcc
	v_cndmask_b32_e32 v1, v1, v3, vcc
	v_add_u32_e32 v3, 1, v2
	v_cmp_ge_u32_e32 vcc, v1, v0
	s_nop 1
	v_cndmask_b32_e32 v2, v2, v3, vcc
	v_mul_lo_u32 v1, v0, v2
	v_add_u32_e32 v0, v1, v0
	v_cmp_ne_u32_e32 vcc, v4, v0
	v_mov_b32_e32 v3, v0
	v_mov_b32_e32 v5, 0x2303000
	v_mov_b64_e32 v[0:1], s[8:9]
	s_and_saveexec_b64 s[6:7], vcc
	s_cbranch_execz .LBB0_271
	v_mov_b32_e32 v0, 0
	global_load_dword v1, v5, s[70:71] offset:1024 sc1
	s_mov_b64 s[18:19], 0
	s_waitcnt vmcnt(0)
	v_cmp_lt_u32_e32 vcc, v1, v3
	s_and_saveexec_b64 s[12:13], vcc
	s_cbranch_execz .LBB0_270
	s_add_u32 s10, s70, 0x2300200
	s_addc_u32 s11, s71, 0
	s_mov_b32 s14, 1
	s_branch .LBB0_263

; __device__ __forceinline__ unsigned xb_ld(unsigned* p)              { return __hip_atomic_load(p, __ATOMIC_RELAXED, __HIP_MEMORY_SCOPE_AGENT); }
; __device__ __forceinline__ unsigned xb_add(unsigned* p, unsigned v) { return __hip_atomic_fetch_add(p, v, __ATOMIC_RELAXED, __HIP_MEMORY_SCOPE_AGENT); }
; #define XB_SPIN(cond, bar) do { unsigned _sp = 0; while (cond) { __builtin_amdgcn_s_sleep(1); \
;     if ((++_sp & 255u) == 0u) { if (xb_ld(&(bar)[XB_TMO])) break; if (_sp > XB_SPIN_CAP) { atomicAdd(&(bar)[XB_TMO], 1u); break; } } } } while (0)
; __device__ __forceinline__ void xcd_barrier(const XcdBarrier& b) {
;     ...
;             const unsigned og = xb_add(&bar[XB_TOP], 1u);
;             const unsigned tg = og / nx;
;             if (og + 1u == (tg + 1u) * nx) xb_add(&bar[XB_TOPGEN], 1u);
;             else XB_SPIN(xb_ld(&bar[XB_TOPGEN]) == tg, bar);
;             __builtin_amdgcn_fence(__ATOMIC_ACQUIRE, "agent");
.LBB0_802:
	s_or_b64 exec, exec, s[10:11]
	buffer_inv sc1
	v_cvt_f32_u32_e32 v3, v0
	s_waitcnt vmcnt(0)
	v_readfirstlane_b32 s3, v2
	s_add_u32 s10, s70, 0x2303500
	s_addc_u32 s11, s71, 0
	v_rcp_iflag_f32_e32 v3, v3
	v_add_u32_e32 v1, s3, v1
	v_add_u32_e32 v4, 1, v1
	s_mov_b64 s[12:13], -1
	v_mul_f32_e32 v2, 0x4f7ffffe, v3
	v_cvt_u32_f32_e32 v2, v2
	v_sub_u32_e32 v3, 0, v0
	v_mul_lo_u32 v3, v3, v2
	v_mul_hi_u32 v3, v2, v3
	v_add_u32_e32 v2, v2, v3
	v_mul_hi_u32 v2, v1, v2
	v_mul_lo_u32 v3, v2, v0
	v_sub_u32_e32 v1, v1, v3
	v_add_u32_e32 v5, 1, v2
	v_cmp_ge_u32_e32 vcc, v1, v0
	v_sub_u32_e32 v3, v1, v0
	s_nop 0
	v_cndmask_b32_e32 v2, v2, v5, vcc
	v_cndmask_b32_e32 v1, v1, v3, vcc
	v_add_u32_e32 v3, 1, v2
	v_cmp_ge_u32_e32 vcc, v1, v0
	s_nop 1
	v_cndmask_b32_e32 v2, v2, v3, vcc
	v_mul_lo_u32 v1, v0, v2
	v_add_u32_e32 v0, v1, v0
	v_cmp_ne_u32_e32 vcc, v4, v0
	v_mov_b32_e32 v3, v0
	v_mov_b32_e32 v5, 0x2303000
	v_mov_b64_e32 v[0:1], s[10:11]
	s_and_saveexec_b64 s[8:9], vcc
	s_cbranch_execz .LBB0_814
	v_mov_b32_e32 v0, 0
	global_load_dword v1, v5, s[70:71] offset:1024 sc1
	s_mov_b64 s[18:19], 0
	s_waitcnt vmcnt(0)
	v_cmp_lt_u32_e32 vcc, v1, v3
	s_and_saveexec_b64 s[14:15], vcc
	s_cbranch_execz .LBB0_813
	s_add_u32 s12, s70, 0x2300200
	s_addc_u32 s13, s71, 0
	s_mov_b32 s3, 1
	s_branch .LBB0_806
